# grid barrier: XCD leader bumps its XCD generation word before its own L1 invalidate instead of after it
# speedup vs baseline: 1.0033x; 1.0033x over previous
; DI unsigned xb_ld(unsigned* p) { return __hip_atomic_load(p, __ATOMIC_RELAXED, __HIP_MEMORY_SCOPE_AGENT); }
; DI unsigned xb_add(unsigned* p, unsigned v) { return __hip_atomic_fetch_add(p, v, __ATOMIC_RELAXED, __HIP_MEMORY_SCOPE_AGENT); }
; #define XB_SPIN(cond, bar) do { unsigned _sp = 0; while (cond) { __builtin_amdgcn_s_sleep(1); \
;     if ((++_sp & 255u) == 0u) { if (xb_ld(&(bar)[XB_TMO])) break; if (_sp > XB_SPIN_CAP) { atomicAdd(&(bar)[XB_TMO], 1u); break; } } } } while (0)
; DI void xcd_barrier(const XcdBarrier& b) {
;     ...
;             __builtin_amdgcn_fence(__ATOMIC_RELEASE, "agent");
;             asm volatile("s_waitcnt vmcnt(0)" ::: "memory");
;             const unsigned og = xb_add(&bar[XB_TOP], 1u);
;             const unsigned tg = og / nx;
;             if (og + 1u == (tg + 1u) * nx) xb_add(&bar[XB_TOPGEN], 1u);
;             else XB_SPIN(xb_ld(&bar[XB_TOPGEN]) == tg, bar);
;             __builtin_amdgcn_fence(__ATOMIC_ACQUIRE, "agent");
;             xb_add(&bar[XB_XGEN(b.x)], 1u);
;             asm volatile("s_waitcnt vmcnt(0)" ::: "memory");
.LBB0_712:
	s_or_b64 exec, exec, s[4:5]
	s_mov_b64 s[4:5], exec
	v_mbcnt_lo_u32_b32 v0, s4, 0
	v_mbcnt_hi_u32_b32 v0, s5, v0
	v_cmp_eq_u32_e32 vcc, 0, v0
	s_and_saveexec_b64 s[6:7], vcc
	s_cbranch_execz .LBB0_714
	s_bcnt1_i32_b64 s4, s[4:5]
	v_mov_b32_e32 v0, 0x2000
	v_mov_b32_e32 v1, s4
	global_atomic_add v0, v1, s[2:3] offset:1024
.LBB0_714:
	s_or_b64 exec, exec, s[6:7]
	buffer_inv sc1
	s_waitcnt vmcnt(0)

; DI unsigned xb_ld(unsigned* p) { return __hip_atomic_load(p, __ATOMIC_RELAXED, __HIP_MEMORY_SCOPE_AGENT); }
; DI unsigned xb_add(unsigned* p, unsigned v) { return __hip_atomic_fetch_add(p, v, __ATOMIC_RELAXED, __HIP_MEMORY_SCOPE_AGENT); }
; #define XB_SPIN(cond, bar) do { unsigned _sp = 0; while (cond) { __builtin_amdgcn_s_sleep(1); \
;     if ((++_sp & 255u) == 0u) { if (xb_ld(&(bar)[XB_TMO])) break; if (_sp > XB_SPIN_CAP) { atomicAdd(&(bar)[XB_TMO], 1u); break; } } } } while (0)
; DI void xcd_barrier(const XcdBarrier& b) {
;     ...
;             __builtin_amdgcn_fence(__ATOMIC_RELEASE, "agent");
;             asm volatile("s_waitcnt vmcnt(0)" ::: "memory");
;             const unsigned og = xb_add(&bar[XB_TOP], 1u);
;             const unsigned tg = og / nx;
;             if (og + 1u == (tg + 1u) * nx) xb_add(&bar[XB_TOPGEN], 1u);
;             else XB_SPIN(xb_ld(&bar[XB_TOPGEN]) == tg, bar);
;             __builtin_amdgcn_fence(__ATOMIC_ACQUIRE, "agent");
;             xb_add(&bar[XB_XGEN(b.x)], 1u);
;             asm volatile("s_waitcnt vmcnt(0)" ::: "memory");
.LBB0_1559:
	s_or_b64 exec, exec, s[6:7]
	s_mov_b64 s[6:7], exec
	v_mbcnt_lo_u32_b32 v0, s6, 0
	v_mbcnt_hi_u32_b32 v0, s7, v0
	v_cmp_eq_u32_e32 vcc, 0, v0
	s_and_saveexec_b64 s[8:9], vcc
	s_cbranch_execz .LBB0_1561
	s_bcnt1_i32_b64 s2, s[6:7]
	v_mov_b32_e32 v0, 0x2000
	v_mov_b32_e32 v1, s2
	global_atomic_add v0, v1, s[4:5] offset:1024
.LBB0_1561:
	s_or_b64 exec, exec, s[8:9]
	buffer_inv sc1
	s_waitcnt vmcnt(0)
